# grid barrier: XCD leaders no longer issue and wait for the two unread generation-word atomics (XGEN/TOPGEN) before leaving the barrier
# speedup vs baseline: 1.0026x; 1.0026x over previous
; __device__ __forceinline__ unsigned xb_ld(unsigned* p)              { return __hip_atomic_load(p, __ATOMIC_RELAXED, __HIP_MEMORY_SCOPE_AGENT); }
; __device__ __forceinline__ unsigned xb_add(unsigned* p, unsigned v) { return __hip_atomic_fetch_add(p, v, __ATOMIC_RELAXED, __HIP_MEMORY_SCOPE_AGENT); }
; #define XB_SPIN(cond, bar) do { unsigned _sp = 0; while (cond) { __builtin_amdgcn_s_sleep(1); \
;     if ((++_sp & 255u) == 0u) { if (xb_ld(&(bar)[XB_TMO])) break; if (_sp > XB_SPIN_CAP) { atomicAdd(&(bar)[XB_TMO], 1u); break; } } } } while (0)
; __device__ __forceinline__ void xcd_barrier(const XcdBarrier& b) {
;     asm volatile("s_waitcnt vmcnt(0)" ::: "memory");
;     __syncthreads();
;     if (threadIdx.x == 0) {
;         unsigned* bar = b.bar;
;         __builtin_amdgcn_s_waitcnt(0);
;         unsigned nloc = b.st[0], nx = b.st[1];
;         if (nloc == 0u) { unsigned bal; xcd_barrier_complete(bar, b.x, nloc, nx, bal); b.st[0] = nloc; b.st[1] = nx; b.st[3] = bal; }
;         const unsigned old = xb_add(&bar[XB_XSUB(b.x)], 1u);
;         const unsigned gen = old / nloc;
;         if (old + 1u == (gen + 1u) * nloc) {
;             __builtin_amdgcn_fence(__ATOMIC_RELEASE, "agent");
;             asm volatile("s_waitcnt vmcnt(0)" ::: "memory");
;             const unsigned og = xb_add(&bar[XB_TOP], 1u);
;             const unsigned tg = og / nx;
;             if (og + 1u == (tg + 1u) * nx) xb_add(&bar[XB_TOPGEN], 1u);
;             else XB_SPIN(xb_ld(&bar[XB_TOPGEN]) == tg, bar);
.LBB0_217:
	s_or_b64 exec, exec, s[10:11]
	v_cvt_f32_u32_e32 v3, v0
	s_waitcnt vmcnt(0)
	v_readfirstlane_b32 s0, v2
	s_add_u32 s10, s78, 0x3500
	s_addc_u32 s11, s79, 0
	v_rcp_iflag_f32_e32 v3, v3
	v_add_u32_e32 v1, s0, v1
	v_add_u32_e32 v4, 1, v1
	s_mov_b64 s[14:15], 0
	v_mul_f32_e32 v2, 0x4f7ffffe, v3
	v_cvt_u32_f32_e32 v2, v2
	v_sub_u32_e32 v3, 0, v0
	v_mul_lo_u32 v3, v3, v2
	v_mul_hi_u32 v3, v2, v3
	v_add_u32_e32 v2, v2, v3
	v_mul_hi_u32 v2, v1, v2
	v_mul_lo_u32 v3, v2, v0
	v_sub_u32_e32 v1, v1, v3
	v_add_u32_e32 v5, 1, v2
	v_cmp_ge_u32_e32 vcc, v1, v0
	v_sub_u32_e32 v3, v1, v0
	s_nop 0
	v_cndmask_b32_e32 v2, v2, v5, vcc
	v_cndmask_b32_e32 v1, v1, v3, vcc
	v_add_u32_e32 v3, 1, v2
	v_cmp_ge_u32_e32 vcc, v1, v0
	s_nop 1
	v_cndmask_b32_e32 v2, v2, v3, vcc
	v_mul_lo_u32 v1, v0, v2
	v_add_u32_e32 v0, v1, v0
	v_cmp_ne_u32_e32 vcc, v4, v0
	v_mov_b32_e32 v2, v0
	v_mov_b64_e32 v[0:1], s[10:11]
	s_and_saveexec_b64 s[8:9], vcc
	s_cbranch_execz .LBB0_229
	v_mov_b32_e32 v0, 0
	global_load_dword v1, v0, s[10:11] offset:-256 sc1
	s_mov_b64 s[18:19], 0
	s_waitcnt vmcnt(0)
	v_cmp_lt_u32_e32 vcc, v1, v2
	s_and_saveexec_b64 s[16:17], vcc
	s_cbranch_execz .LBB0_228
	s_add_u32 s14, s78, 0x200
	s_addc_u32 s15, s79, 0
	s_mov_b32 s0, 1
	s_branch .LBB0_221

; __device__ __forceinline__ unsigned xb_add(unsigned* p, unsigned v) { return __hip_atomic_fetch_add(p, v, __ATOMIC_RELAXED, __HIP_MEMORY_SCOPE_AGENT); }
; __device__ __forceinline__ void xcd_barrier(const XcdBarrier& b) {
;     ...
;             xb_add(&bar[XB_XGEN(b.x)], 1u);
;             asm volatile("s_waitcnt vmcnt(0)" ::: "memory");
.LBB0_231:
	s_or_b64 exec, exec, s[8:9]
	s_mov_b64 s[8:9], exec
	v_mbcnt_lo_u32_b32 v0, s8, 0
	v_mbcnt_hi_u32_b32 v0, s9, v0
	v_cmp_eq_u32_e32 vcc, 0, v0
	s_waitcnt vmcnt(0)
	buffer_inv sc1
	s_and_saveexec_b64 s[10:11], vcc
	s_cbranch_execz .LBB0_233
	s_bcnt1_i32_b64 s0, s[8:9]
	v_mov_b32_e32 v0, 0x2000
	v_mov_b32_e32 v1, s0
.LBB0_233:
	s_or_b64 exec, exec, s[10:11]
	s_waitcnt vmcnt(0)

; __device__ __forceinline__ unsigned xb_add(unsigned* p, unsigned v) { return __hip_atomic_fetch_add(p, v, __ATOMIC_RELAXED, __HIP_MEMORY_SCOPE_AGENT); }
; __device__ __forceinline__ void xcd_barrier(const XcdBarrier& b) {
;     ...
;             xb_add(&bar[XB_XGEN(b.x)], 1u);
;             asm volatile("s_waitcnt vmcnt(0)" ::: "memory");
.LBB0_285:
	s_or_b64 exec, exec, s[8:9]
	s_mov_b64 s[8:9], exec
	v_mbcnt_lo_u32_b32 v0, s8, 0
	v_mbcnt_hi_u32_b32 v0, s9, v0
	v_cmp_eq_u32_e32 vcc, 0, v0
	s_waitcnt vmcnt(0)
	buffer_inv sc1
	s_and_saveexec_b64 s[10:11], vcc
	s_cbranch_execz .LBB0_287
	s_bcnt1_i32_b64 s0, s[8:9]
	v_mov_b32_e32 v0, 0x2000
	v_mov_b32_e32 v1, s0
.LBB0_287:
	s_or_b64 exec, exec, s[10:11]
	s_waitcnt vmcnt(0)

; __device__ __forceinline__ unsigned xb_add(unsigned* p, unsigned v) { return __hip_atomic_fetch_add(p, v, __ATOMIC_RELAXED, __HIP_MEMORY_SCOPE_AGENT); }
; __device__ __forceinline__ void xcd_barrier(const XcdBarrier& b) {
;     ...
;             xb_add(&bar[XB_XGEN(b.x)], 1u);
;             asm volatile("s_waitcnt vmcnt(0)" ::: "memory");
.LBB0_373:
	s_or_b64 exec, exec, s[8:9]
	s_mov_b64 s[8:9], exec
	v_mbcnt_lo_u32_b32 v0, s8, 0
	v_mbcnt_hi_u32_b32 v0, s9, v0
	v_cmp_eq_u32_e32 vcc, 0, v0
	s_waitcnt vmcnt(0)
	buffer_inv sc1
	s_and_saveexec_b64 s[10:11], vcc
	s_cbranch_execz .LBB0_375
	s_bcnt1_i32_b64 s0, s[8:9]
	v_mov_b32_e32 v0, 0x2000
	v_mov_b32_e32 v1, s0
.LBB0_375:
	s_or_b64 exec, exec, s[10:11]
	s_waitcnt vmcnt(0)

; __device__ __forceinline__ unsigned xb_add(unsigned* p, unsigned v) { return __hip_atomic_fetch_add(p, v, __ATOMIC_RELAXED, __HIP_MEMORY_SCOPE_AGENT); }
; __device__ __forceinline__ void xcd_barrier(const XcdBarrier& b) {
;     ...
;             xb_add(&bar[XB_XGEN(b.x)], 1u);
;             asm volatile("s_waitcnt vmcnt(0)" ::: "memory");
.LBB0_445:
	s_or_b64 exec, exec, s[8:9]
	s_mov_b64 s[8:9], exec
	v_mbcnt_lo_u32_b32 v0, s8, 0
	v_mbcnt_hi_u32_b32 v0, s9, v0
	v_cmp_eq_u32_e32 vcc, 0, v0
	s_waitcnt vmcnt(0)
	buffer_inv sc1
	s_and_saveexec_b64 s[10:11], vcc
	s_cbranch_execz .LBB0_447
	s_bcnt1_i32_b64 s0, s[8:9]
	v_mov_b32_e32 v0, 0x2000
	v_mov_b32_e32 v1, s0
.LBB0_447:
	s_or_b64 exec, exec, s[10:11]
	s_waitcnt vmcnt(0)

; __device__ __forceinline__ unsigned xb_ld(unsigned* p)              { return __hip_atomic_load(p, __ATOMIC_RELAXED, __HIP_MEMORY_SCOPE_AGENT); }
; __device__ __forceinline__ unsigned xb_add(unsigned* p, unsigned v) { return __hip_atomic_fetch_add(p, v, __ATOMIC_RELAXED, __HIP_MEMORY_SCOPE_AGENT); }
; #define XB_SPIN(cond, bar) do { unsigned _sp = 0; while (cond) { __builtin_amdgcn_s_sleep(1); \
;     if ((++_sp & 255u) == 0u) { if (xb_ld(&(bar)[XB_TMO])) break; if (_sp > XB_SPIN_CAP) { atomicAdd(&(bar)[XB_TMO], 1u); break; } } } } while (0)
; __device__ __forceinline__ void xcd_barrier(const XcdBarrier& b) {
;     asm volatile("s_waitcnt vmcnt(0)" ::: "memory");
;     __syncthreads();
;     if (threadIdx.x == 0) {
;         unsigned* bar = b.bar;
;         __builtin_amdgcn_s_waitcnt(0);
;         unsigned nloc = b.st[0], nx = b.st[1];
;         if (nloc == 0u) { unsigned bal; xcd_barrier_complete(bar, b.x, nloc, nx, bal); b.st[0] = nloc; b.st[1] = nx; b.st[3] = bal; }
;         const unsigned old = xb_add(&bar[XB_XSUB(b.x)], 1u);
;         const unsigned gen = old / nloc;
;         if (old + 1u == (gen + 1u) * nloc) {
;             __builtin_amdgcn_fence(__ATOMIC_RELEASE, "agent");
;             asm volatile("s_waitcnt vmcnt(0)" ::: "memory");
;             const unsigned og = xb_add(&bar[XB_TOP], 1u);
;             const unsigned tg = og / nx;
;             if (og + 1u == (tg + 1u) * nx) xb_add(&bar[XB_TOPGEN], 1u);
;             else XB_SPIN(xb_ld(&bar[XB_TOPGEN]) == tg, bar);
.LBB0_574:
	s_or_b64 exec, exec, s[10:11]
	v_cvt_f32_u32_e32 v3, v0
	s_waitcnt vmcnt(0)
	v_readfirstlane_b32 s0, v2
	s_add_u32 s10, s78, 0x3500
	s_addc_u32 s11, s79, 0
	v_rcp_iflag_f32_e32 v3, v3
	v_add_u32_e32 v1, s0, v1
	v_add_u32_e32 v4, 1, v1
	s_mov_b64 s[12:13], 0
	v_mul_f32_e32 v2, 0x4f7ffffe, v3
	v_cvt_u32_f32_e32 v2, v2
	v_sub_u32_e32 v3, 0, v0
	v_mul_lo_u32 v3, v3, v2
	v_mul_hi_u32 v3, v2, v3
	v_add_u32_e32 v2, v2, v3
	v_mul_hi_u32 v2, v1, v2
	v_mul_lo_u32 v3, v2, v0
	v_sub_u32_e32 v1, v1, v3
	v_add_u32_e32 v5, 1, v2
	v_cmp_ge_u32_e32 vcc, v1, v0
	v_sub_u32_e32 v3, v1, v0
	s_nop 0
	v_cndmask_b32_e32 v2, v2, v5, vcc
	v_cndmask_b32_e32 v1, v1, v3, vcc
	v_add_u32_e32 v3, 1, v2
	v_cmp_ge_u32_e32 vcc, v1, v0
	s_nop 1
	v_cndmask_b32_e32 v2, v2, v3, vcc
	v_mul_lo_u32 v1, v0, v2
	v_add_u32_e32 v0, v1, v0
	v_cmp_ne_u32_e32 vcc, v4, v0
	v_mov_b32_e32 v2, v0
	v_mov_b64_e32 v[0:1], s[10:11]
	s_and_saveexec_b64 s[8:9], vcc
	s_cbranch_execz .LBB0_586
	v_mov_b32_e32 v0, 0
	global_load_dword v1, v0, s[10:11] offset:-256 sc1
	s_mov_b64 s[16:17], 0
	s_waitcnt vmcnt(0)
	v_cmp_lt_u32_e32 vcc, v1, v2
	s_and_saveexec_b64 s[14:15], vcc
	s_cbranch_execz .LBB0_585
	s_add_u32 s12, s78, 0x200
	s_addc_u32 s13, s79, 0
	s_mov_b32 s0, 1
	s_branch .LBB0_578

; __device__ __forceinline__ unsigned xb_add(unsigned* p, unsigned v) { return __hip_atomic_fetch_add(p, v, __ATOMIC_RELAXED, __HIP_MEMORY_SCOPE_AGENT); }
; __device__ __forceinline__ void xcd_barrier(const XcdBarrier& b) {
;     ...
;             xb_add(&bar[XB_XGEN(b.x)], 1u);
;             asm volatile("s_waitcnt vmcnt(0)" ::: "memory");
.LBB0_588:
	s_or_b64 exec, exec, s[8:9]
	s_mov_b64 s[8:9], exec
	v_mbcnt_lo_u32_b32 v0, s8, 0
	v_mbcnt_hi_u32_b32 v0, s9, v0
	v_cmp_eq_u32_e32 vcc, 0, v0
	s_waitcnt vmcnt(0)
	buffer_inv sc1
	s_and_saveexec_b64 s[10:11], vcc
	s_cbranch_execz .LBB0_590
	s_bcnt1_i32_b64 s0, s[8:9]
	v_mov_b32_e32 v0, 0x2000
	v_mov_b32_e32 v1, s0
.LBB0_590:
	s_or_b64 exec, exec, s[10:11]
	s_waitcnt vmcnt(0)

; __device__ __forceinline__ unsigned xb_add(unsigned* p, unsigned v) { return __hip_atomic_fetch_add(p, v, __ATOMIC_RELAXED, __HIP_MEMORY_SCOPE_AGENT); }
; __device__ __forceinline__ void xcd_barrier(const XcdBarrier& b) {
;     ...
;             xb_add(&bar[XB_XGEN(b.x)], 1u);
;             asm volatile("s_waitcnt vmcnt(0)" ::: "memory");
.LBB0_697:
	s_or_b64 exec, exec, s[8:9]
	s_mov_b64 s[8:9], exec
	v_mbcnt_lo_u32_b32 v0, s8, 0
	v_mbcnt_hi_u32_b32 v0, s9, v0
	v_cmp_eq_u32_e32 vcc, 0, v0
	s_waitcnt vmcnt(0)
	buffer_inv sc1
	s_and_saveexec_b64 s[10:11], vcc
	s_cbranch_execz .LBB0_699
	s_bcnt1_i32_b64 s0, s[8:9]
	v_mov_b32_e32 v0, 0x2000
	v_mov_b32_e32 v1, s0
.LBB0_699:
	s_or_b64 exec, exec, s[10:11]
	s_waitcnt vmcnt(0)

; __device__ __forceinline__ unsigned xb_add(unsigned* p, unsigned v) { return __hip_atomic_fetch_add(p, v, __ATOMIC_RELAXED, __HIP_MEMORY_SCOPE_AGENT); }
; __device__ __forceinline__ void xcd_barrier(const XcdBarrier& b) {
;     ...
;             xb_add(&bar[XB_XGEN(b.x)], 1u);
;             asm volatile("s_waitcnt vmcnt(0)" ::: "memory");
.LBB0_771:
	s_or_b64 exec, exec, s[8:9]
	s_mov_b64 s[8:9], exec
	v_mbcnt_lo_u32_b32 v0, s8, 0
	v_mbcnt_hi_u32_b32 v0, s9, v0
	v_cmp_eq_u32_e32 vcc, 0, v0
	s_waitcnt vmcnt(0)
	buffer_inv sc1
	s_and_saveexec_b64 s[10:11], vcc
	s_cbranch_execz .LBB0_773
	s_bcnt1_i32_b64 s0, s[8:9]
	v_mov_b32_e32 v0, 0x2000
	v_mov_b32_e32 v1, s0
.LBB0_773:
	s_or_b64 exec, exec, s[10:11]
	s_waitcnt vmcnt(0)

; __device__ __forceinline__ unsigned xb_add(unsigned* p, unsigned v) { return __hip_atomic_fetch_add(p, v, __ATOMIC_RELAXED, __HIP_MEMORY_SCOPE_AGENT); }
; __device__ __forceinline__ void xcd_barrier(const XcdBarrier& b) {
;     ...
;             xb_add(&bar[XB_XGEN(b.x)], 1u);
;             asm volatile("s_waitcnt vmcnt(0)" ::: "memory");
.LBB0_849:
	s_or_b64 exec, exec, s[8:9]
	s_mov_b64 s[8:9], exec
	v_mbcnt_lo_u32_b32 v0, s8, 0
	v_mbcnt_hi_u32_b32 v0, s9, v0
	v_cmp_eq_u32_e32 vcc, 0, v0
	s_waitcnt vmcnt(0)
	buffer_inv sc1
	s_and_saveexec_b64 s[10:11], vcc
	s_cbranch_execz .LBB0_851
	s_bcnt1_i32_b64 s0, s[8:9]
	v_mov_b32_e32 v0, 0x2000
	v_mov_b32_e32 v1, s0
.LBB0_851:
	s_or_b64 exec, exec, s[10:11]
	s_waitcnt vmcnt(0)

; __device__ __forceinline__ unsigned xb_add(unsigned* p, unsigned v) { return __hip_atomic_fetch_add(p, v, __ATOMIC_RELAXED, __HIP_MEMORY_SCOPE_AGENT); }
; __device__ __forceinline__ void xcd_barrier(const XcdBarrier& b) {
;     ...
;             xb_add(&bar[XB_XGEN(b.x)], 1u);
;             asm volatile("s_waitcnt vmcnt(0)" ::: "memory");
.LBB0_903:
	s_or_b64 exec, exec, s[8:9]
	s_mov_b64 s[8:9], exec
	v_mbcnt_lo_u32_b32 v0, s8, 0
	v_mbcnt_hi_u32_b32 v0, s9, v0
	v_cmp_eq_u32_e32 vcc, 0, v0
	s_waitcnt vmcnt(0)
	buffer_inv sc1
	s_and_saveexec_b64 s[10:11], vcc
	s_cbranch_execz .LBB0_905
	s_bcnt1_i32_b64 s0, s[8:9]
	v_mov_b32_e32 v0, 0x2000
	v_mov_b32_e32 v1, s0
.LBB0_905:
	s_or_b64 exec, exec, s[10:11]
	s_waitcnt vmcnt(0)

; __device__ __forceinline__ unsigned xb_add(unsigned* p, unsigned v) { return __hip_atomic_fetch_add(p, v, __ATOMIC_RELAXED, __HIP_MEMORY_SCOPE_AGENT); }
; __device__ __forceinline__ void xcd_barrier(const XcdBarrier& b) {
;     ...
;             xb_add(&bar[XB_XGEN(b.x)], 1u);
;             asm volatile("s_waitcnt vmcnt(0)" ::: "memory");
.LBB0_970:
	s_or_b64 exec, exec, s[8:9]
	s_mov_b64 s[8:9], exec
	v_mbcnt_lo_u32_b32 v0, s8, 0
	v_mbcnt_hi_u32_b32 v0, s9, v0
	v_cmp_eq_u32_e32 vcc, 0, v0
	s_waitcnt vmcnt(0)
	buffer_inv sc1
	s_and_saveexec_b64 s[10:11], vcc
	s_cbranch_execz .LBB0_972
	s_bcnt1_i32_b64 s0, s[8:9]
	v_mov_b32_e32 v0, 0x2000
	v_mov_b32_e32 v1, s0
.LBB0_972:
	s_or_b64 exec, exec, s[10:11]
	s_waitcnt vmcnt(0)

; __device__ __forceinline__ unsigned xb_add(unsigned* p, unsigned v) { return __hip_atomic_fetch_add(p, v, __ATOMIC_RELAXED, __HIP_MEMORY_SCOPE_AGENT); }
; __device__ __forceinline__ void xcd_barrier(const XcdBarrier& b) {
;     ...
;             xb_add(&bar[XB_XGEN(b.x)], 1u);
;             asm volatile("s_waitcnt vmcnt(0)" ::: "memory");
.LBB0_1037:
	s_or_b64 exec, exec, s[8:9]
	s_mov_b64 s[8:9], exec
	v_mbcnt_lo_u32_b32 v0, s8, 0
	v_mbcnt_hi_u32_b32 v0, s9, v0
	v_cmp_eq_u32_e32 vcc, 0, v0
	s_waitcnt vmcnt(0)
	buffer_inv sc1
	s_and_saveexec_b64 s[10:11], vcc
	s_cbranch_execz .LBB0_1039
	s_bcnt1_i32_b64 s0, s[8:9]
	v_mov_b32_e32 v0, 0x2000
	v_mov_b32_e32 v1, s0
.LBB0_1039:
	s_or_b64 exec, exec, s[10:11]
	s_waitcnt vmcnt(0)
